# v_combo8 + PEER V loops: first accumulation of each int32 accumulator as v_dot4_i32_i8 acc,a,b,0 instead of zeroing v_mov + v_dot4c (48 VALU fewer per loop trip)
# speedup vs baseline: 1.0032x; 1.0032x over previous
.LBB0_1394:
	s_add_i32 s1, s33, 2
	s_lshr_b32 s45, s1, 4
	s_lshl_b32 s40, s45, 21
	s_add_u32 s48, s36, s40
	s_waitcnt lgkmcnt(1)
	v_lshlrev_b32_e32 v76, 7, v72
	v_bfe_u32 v72, v72, 16, 16
	s_addc_u32 s49, s37, 0
	v_and_or_b32 v76, v76, s68, v150
	v_lshl_or_b32 v72, v72, 7, v150
	global_load_dwordx4 v[128:131], v76, s[48:49]
	global_load_dwordx4 v[132:135], v72, s[48:49]
	v_lshlrev_b32_e32 v72, 7, v73
	v_and_or_b32 v72, v72, s68, v150
	v_bfe_u32 v73, v73, 16, 16
	v_lshl_or_b32 v73, v73, 7, v150
	global_load_dwordx4 v[136:139], v72, s[48:49]
	global_load_dwordx4 v[140:143], v73, s[48:49]
	v_lshlrev_b32_e32 v72, 7, v74
	v_and_or_b32 v72, v72, s68, v150
	v_bfe_u32 v73, v74, 16, 16
	v_lshl_or_b32 v73, v73, 7, v150
	global_load_dwordx4 v[112:115], v72, s[48:49]
	global_load_dwordx4 v[116:119], v73, s[48:49]
	v_lshlrev_b32_e32 v72, 7, v75
	v_and_or_b32 v72, v72, s68, v150
	v_bfe_u32 v73, v75, 16, 16
	v_lshl_or_b32 v73, v73, 7, v150
	global_load_dwordx4 v[120:123], v72, s[48:49]
	global_load_dwordx4 v[124:127], v73, s[48:49]
	s_waitcnt lgkmcnt(0)
	v_lshlrev_b32_e32 v72, 7, v68
	v_bfe_u32 v68, v68, 16, 16
	v_and_or_b32 v72, v72, s68, v150
	v_lshl_or_b32 v68, v68, 7, v150
	global_load_dwordx4 v[96:99], v72, s[48:49]
	global_load_dwordx4 v[100:103], v68, s[48:49]
	v_lshlrev_b32_e32 v68, 7, v69
	v_and_or_b32 v68, v68, s68, v150
	v_bfe_u32 v69, v69, 16, 16
	v_lshl_or_b32 v69, v69, 7, v150
	global_load_dwordx4 v[104:107], v68, s[48:49]
	global_load_dwordx4 v[108:111], v69, s[48:49]
	v_lshlrev_b32_e32 v68, 7, v70
	v_and_or_b32 v68, v68, s68, v150
	v_bfe_u32 v69, v70, 16, 16
	v_lshl_or_b32 v69, v69, 7, v150
	global_load_dwordx4 v[76:79], v68, s[48:49]
	global_load_dwordx4 v[80:83], v69, s[48:49]
	v_lshlrev_b32_e32 v68, 7, v71
	v_and_or_b32 v68, v68, s68, v150
	v_bfe_u32 v69, v71, 16, 16
	v_lshl_or_b32 v69, v69, 7, v150
	global_load_dwordx4 v[84:87], v68, s[48:49]
	global_load_dwordx4 v[88:91], v69, s[48:49]
	s_and_b32 s48, s1, 14
	s_or_b32 s49, s48, 1
	s_lshl_b32 s40, s49, 11
	v_lshl_add_u64 v[68:69], v[166:167], 0, s[40:41]
	s_lshl_b32 s40, s45, 8
	v_lshl_add_u64 v[168:169], v[68:69], 0, s[40:41]
	global_load_dword v221, v[168:169], off
	s_add_i32 s45, s33, 4
	s_and_b32 s33, s45, 14
	v_lshl_add_u32 v68, s49, 7, v187
	ds_read_b128 v[92:95], v68
	v_lshl_add_u32 v68, s33, 8, v185
	ds_read_b128 v[72:75], v68
	ds_read_b128 v[68:71], v68 offset:16
	s_lshr_b32 s45, s45, 4
	s_lshl_b32 s49, s45, 21
	s_waitcnt vmcnt(18)
	v_perm_b32 v145, v52, v64, s71
	v_perm_b32 v52, v52, v64, s72
	v_perm_b32 v64, v60, v56, s71
	v_perm_b32 v56, v60, v56, s72
	v_perm_b32 v60, v64, v145, s73
	v_dot4_i32_i8 v144, v60, v12, 0
	v_perm_b32 v60, v64, v145, s74
	v_mov_b32_e32 v145, 0
	v_dot4c_i32_i8_e32 v145, v60, v12
	v_perm_b32 v60, v56, v52, s73
	v_perm_b32 v52, v56, v52, s74
	v_dot4_i32_i8 v147, v52, v12, 0
	v_perm_b32 v52, v53, v65, s71
	v_perm_b32 v56, v61, v57, s71
	v_dot4_i32_i8 v146, v60, v12, 0
	v_perm_b32 v53, v53, v65, s72
	v_perm_b32 v57, v61, v57, s72
	v_perm_b32 v60, v56, v52, s73
	v_perm_b32 v52, v56, v52, s74
	v_dot4_i32_i8 v223, v52, v12, 0
	v_perm_b32 v52, v57, v53, s73
	v_dot4_i32_i8 v224, v52, v12, 0
	v_perm_b32 v52, v57, v53, s74
	v_dot4_i32_i8 v225, v52, v12, 0
	v_perm_b32 v52, v54, v66, s71
	v_perm_b32 v53, v54, v66, s72
	v_perm_b32 v54, v62, v58, s71
	v_perm_b32 v56, v62, v58, s72
	v_perm_b32 v57, v54, v52, s73
	v_perm_b32 v52, v54, v52, s74
	v_dot4_i32_i8 v227, v52, v12, 0
	v_perm_b32 v52, v56, v53, s73
	v_dot4_i32_i8 v228, v52, v12, 0
	v_perm_b32 v52, v56, v53, s74
	v_perm_b32 v53, v55, v67, s71
	v_perm_b32 v54, v63, v59, s71
	v_dot4_i32_i8 v226, v57, v12, 0
	v_dot4_i32_i8 v229, v52, v12, 0
	v_perm_b32 v55, v55, v67, s72
	v_perm_b32 v56, v63, v59, s72
	v_perm_b32 v57, v54, v53, s73
	v_perm_b32 v54, v54, v53, s74
	v_mov_b32_e32 v53, 0
	v_dot4_i32_i8 v52, v57, v12, 0
	v_dot4c_i32_i8_e32 v53, v54, v12
	v_perm_b32 v57, v56, v55, s73
	v_mov_b32_e32 v54, 0
	v_perm_b32 v56, v56, v55, s74
	v_mov_b32_e32 v55, 0
	v_dot4_i32_i8 v222, v60, v12, 0
	v_dot4c_i32_i8_e32 v54, v57, v12
	v_dot4c_i32_i8_e32 v55, v56, v12
	v_perm_b32 v12, v40, v36, s71
	v_perm_b32 v36, v40, v36, s72
	v_perm_b32 v40, v48, v44, s71
	v_perm_b32 v44, v48, v44, s72
	v_perm_b32 v48, v40, v12, s73
	v_perm_b32 v12, v40, v12, s74
	v_dot4c_i32_i8_e32 v145, v12, v13
	v_perm_b32 v12, v44, v36, s73
	v_dot4c_i32_i8_e32 v146, v12, v13
	v_perm_b32 v12, v44, v36, s74
	v_dot4c_i32_i8_e32 v147, v12, v13
	v_perm_b32 v12, v41, v37, s71
	v_perm_b32 v36, v41, v37, s72
	v_perm_b32 v37, v49, v45, s71
	v_perm_b32 v40, v49, v45, s72
	v_perm_b32 v41, v37, v12, s73
	v_perm_b32 v12, v37, v12, s74
	v_dot4c_i32_i8_e32 v223, v12, v13
	v_perm_b32 v12, v40, v36, s73
	v_dot4c_i32_i8_e32 v224, v12, v13
	v_perm_b32 v12, v40, v36, s74
	v_dot4c_i32_i8_e32 v225, v12, v13
	v_perm_b32 v12, v42, v38, s71
	v_perm_b32 v37, v50, v46, s71
	v_perm_b32 v36, v42, v38, s72
	v_perm_b32 v38, v50, v46, s72
	v_perm_b32 v40, v37, v12, s73
	v_perm_b32 v12, v37, v12, s74
	v_dot4c_i32_i8_e32 v227, v12, v13
	v_perm_b32 v12, v38, v36, s73
	v_dot4c_i32_i8_e32 v228, v12, v13
	v_perm_b32 v12, v38, v36, s74
	v_dot4c_i32_i8_e32 v229, v12, v13
	v_perm_b32 v12, v43, v39, s71
	v_perm_b32 v37, v51, v47, s71
	v_perm_b32 v36, v43, v39, s72
	v_perm_b32 v38, v51, v47, s72
	v_perm_b32 v39, v37, v12, s73
	v_perm_b32 v12, v37, v12, s74
	v_dot4c_i32_i8_e32 v53, v12, v13
	v_perm_b32 v12, v38, v36, s73
	v_dot4c_i32_i8_e32 v54, v12, v13
	v_perm_b32 v12, v38, v36, s74
	v_dot4c_i32_i8_e32 v144, v48, v13
	v_dot4c_i32_i8_e32 v222, v41, v13
	v_dot4c_i32_i8_e32 v226, v40, v13
	v_dot4c_i32_i8_e32 v52, v39, v13
	v_dot4c_i32_i8_e32 v55, v12, v13
	v_perm_b32 v12, v24, v20, s71
	v_perm_b32 v13, v24, v20, s72
	v_perm_b32 v20, v32, v28, s71
	v_perm_b32 v24, v32, v28, s72
	v_perm_b32 v28, v20, v12, s73
	v_perm_b32 v12, v20, v12, s74
	v_dot4c_i32_i8_e32 v145, v12, v14
	v_perm_b32 v12, v24, v13, s73
	v_dot4c_i32_i8_e32 v146, v12, v14
	v_perm_b32 v12, v24, v13, s74
	v_dot4c_i32_i8_e32 v147, v12, v14
	v_perm_b32 v12, v25, v21, s71
	v_perm_b32 v20, v33, v29, s71
	v_perm_b32 v13, v25, v21, s72
	v_perm_b32 v21, v33, v29, s72
	v_perm_b32 v24, v20, v12, s73
	v_perm_b32 v12, v20, v12, s74
	v_dot4c_i32_i8_e32 v223, v12, v14
	v_perm_b32 v12, v21, v13, s73
	v_dot4c_i32_i8_e32 v224, v12, v14
	v_perm_b32 v12, v21, v13, s74
	v_dot4c_i32_i8_e32 v225, v12, v14
	v_perm_b32 v12, v26, v22, s71
	v_perm_b32 v20, v34, v30, s71
	v_perm_b32 v13, v26, v22, s72
	v_perm_b32 v21, v34, v30, s72
	v_perm_b32 v22, v20, v12, s73
	v_perm_b32 v12, v20, v12, s74
	v_dot4c_i32_i8_e32 v227, v12, v14
	v_perm_b32 v12, v21, v13, s73
	v_dot4c_i32_i8_e32 v228, v12, v14
	v_perm_b32 v12, v21, v13, s74
	v_dot4c_i32_i8_e32 v229, v12, v14
	v_perm_b32 v12, v27, v23, s71
	v_perm_b32 v20, v35, v31, s71
	v_dot4c_i32_i8_e32 v226, v22, v14
	v_perm_b32 v13, v27, v23, s72
	v_perm_b32 v21, v35, v31, s72
	v_perm_b32 v22, v20, v12, s73
	v_perm_b32 v12, v20, v12, s74
	v_dot4c_i32_i8_e32 v53, v12, v14
	v_perm_b32 v12, v21, v13, s73
	v_dot4c_i32_i8_e32 v54, v12, v14
	v_perm_b32 v12, v21, v13, s74
	v_dot4c_i32_i8_e32 v55, v12, v14
	v_perm_b32 v12, v4, v0, s71
	v_perm_b32 v0, v4, v0, s72
	v_perm_b32 v4, v16, v8, s71
	v_perm_b32 v8, v16, v8, s72
	v_perm_b32 v13, v4, v12, s73
	v_perm_b32 v4, v4, v12, s74
	v_dot4c_i32_i8_e32 v145, v4, v15
	v_perm_b32 v4, v8, v0, s73
	v_perm_b32 v0, v8, v0, s74
	v_dot4c_i32_i8_e32 v146, v4, v15
	v_dot4c_i32_i8_e32 v147, v0, v15
	v_perm_b32 v0, v5, v1, s71
	v_perm_b32 v4, v17, v9, s71
	v_perm_b32 v1, v5, v1, s72
	v_perm_b32 v5, v17, v9, s72
	v_perm_b32 v8, v4, v0, s73
	v_perm_b32 v0, v4, v0, s74
	v_dot4c_i32_i8_e32 v223, v0, v15
	v_perm_b32 v0, v5, v1, s73
	v_dot4c_i32_i8_e32 v224, v0, v15
	v_perm_b32 v0, v5, v1, s74
	v_dot4c_i32_i8_e32 v225, v0, v15
	v_perm_b32 v0, v6, v2, s71
	v_perm_b32 v1, v6, v2, s72
	v_perm_b32 v2, v18, v10, s71
	v_perm_b32 v4, v18, v10, s72
	v_perm_b32 v5, v2, v0, s73
	v_perm_b32 v0, v2, v0, s74
	v_dot4c_i32_i8_e32 v227, v0, v15
	v_perm_b32 v0, v4, v1, s73
	v_dot4c_i32_i8_e32 v228, v0, v15
	v_perm_b32 v0, v4, v1, s74
	v_dot4c_i32_i8_e32 v229, v0, v15
	v_perm_b32 v0, v7, v3, s71
	v_perm_b32 v2, v19, v11, s71
	v_perm_b32 v1, v7, v3, s72
	v_perm_b32 v3, v19, v11, s72
	v_perm_b32 v4, v2, v0, s73
	v_perm_b32 v0, v2, v0, s74
	v_dot4c_i32_i8_e32 v144, v28, v14
	v_dot4c_i32_i8_e32 v53, v0, v15
	v_perm_b32 v0, v3, v1, s73
	v_dot4c_i32_i8_e32 v222, v24, v14
	v_dot4c_i32_i8_e32 v52, v22, v14
	v_dot4c_i32_i8_e32 v144, v13, v15
	v_dot4c_i32_i8_e32 v54, v0, v15
	v_perm_b32 v0, v3, v1, s74
	v_dot4c_i32_i8_e32 v222, v8, v15
	v_dot4c_i32_i8_e32 v226, v5, v15
	v_dot4c_i32_i8_e32 v52, v4, v15
	v_dot4c_i32_i8_e32 v55, v0, v15
	ds_write_b128 v219, v[144:147] offset:2048
	ds_write_b128 v219, v[222:225] offset:2064
	ds_write_b128 v219, v[226:229] offset:2080
	ds_write_b128 v219, v[52:55] offset:2096
	ds_read2st64_b64 v[0:3], v188 offset0:4 offset1:5
	ds_read2st64_b64 v[4:7], v188 offset0:6 offset1:7
	ds_read2st64_b64 v[8:11], v188 offset0:8 offset1:9
	ds_read2st64_b64 v[12:15], v188 offset0:10 offset1:11
	s_add_u32 s50, s36, s49
	s_addc_u32 s51, s37, 0
	s_lshl_b32 s49, s48, 2
	s_waitcnt lgkmcnt(3)
	v_add_u32_e32 v1, v3, v1
	v_add_u32_e32 v0, v2, v0
	s_add_i32 s49, s64, s49
	s_waitcnt lgkmcnt(2)
	v_add3_u32 v0, v0, v4, v6
	v_add3_u32 v1, v1, v5, v7
	v_mov_b32_e32 v230, s49
	s_waitcnt lgkmcnt(1)
	v_add3_u32 v1, v1, v9, v11
	v_add3_u32 v0, v0, v8, v10
	ds_read_b32 v16, v230
	s_waitcnt lgkmcnt(1)
	v_add3_u32 v0, v0, v12, v14
	v_add3_u32 v1, v1, v13, v15
	v_cvt_f32_i32_e32 v1, v1
	v_cvt_f32_i32_e32 v0, v0
	s_waitcnt vmcnt(17)
	v_lshlrev_b32_e32 v2, 16, v220
	v_and_b32_e32 v3, 0xffff0000, v220
	s_lshl_b32 s48, s48, 11
	s_waitcnt lgkmcnt(0)
	v_pk_fma_f32 v[0:1], v[16:17], v[0:1], v[2:3] op_sel_hi:[0,1,1]
	s_mov_b32 s49, s41
	v_cvt_pk_bf16_f32 v2, v0, v1
	v_lshl_add_u64 v[0:1], v[166:167], 0, s[48:49]
	v_lshl_add_u64 v[0:1], v[0:1], 0, s[40:41]
	global_store_dword v[0:1], v2, off
	v_lshlrev_b32_e32 v0, 7, v72
	v_bfe_u32 v1, v72, 16, 16
	v_and_or_b32 v0, v0, s68, v150
	v_lshl_or_b32 v1, v1, 7, v150
	global_load_dwordx4 v[64:67], v0, s[50:51]
	global_load_dwordx4 v[52:55], v1, s[50:51]
	v_lshlrev_b32_e32 v0, 7, v73
	v_bfe_u32 v1, v73, 16, 16
	v_and_or_b32 v0, v0, s68, v150
	v_lshl_or_b32 v1, v1, 7, v150
	global_load_dwordx4 v[56:59], v0, s[50:51]
	global_load_dwordx4 v[60:63], v1, s[50:51]
	v_lshlrev_b32_e32 v0, 7, v74
	v_bfe_u32 v1, v74, 16, 16
	v_and_or_b32 v0, v0, s68, v150
	v_lshl_or_b32 v1, v1, 7, v150
	global_load_dwordx4 v[36:39], v0, s[50:51]
	global_load_dwordx4 v[40:43], v1, s[50:51]
	v_lshlrev_b32_e32 v0, 7, v75
	v_bfe_u32 v1, v75, 16, 16
	v_and_or_b32 v0, v0, s68, v150
	v_lshl_or_b32 v1, v1, 7, v150
	global_load_dwordx4 v[44:47], v0, s[50:51]
	global_load_dwordx4 v[48:51], v1, s[50:51]
	v_lshlrev_b32_e32 v0, 7, v68
	v_bfe_u32 v1, v68, 16, 16
	v_and_or_b32 v0, v0, s68, v150
	v_lshl_or_b32 v1, v1, 7, v150
	global_load_dwordx4 v[20:23], v0, s[50:51]
	global_load_dwordx4 v[24:27], v1, s[50:51]
	v_lshlrev_b32_e32 v0, 7, v69
	v_bfe_u32 v1, v69, 16, 16
	v_and_or_b32 v0, v0, s68, v150
	v_lshl_or_b32 v1, v1, 7, v150
	global_load_dwordx4 v[28:31], v0, s[50:51]
	global_load_dwordx4 v[32:35], v1, s[50:51]
	v_lshlrev_b32_e32 v0, 7, v70
	v_bfe_u32 v1, v70, 16, 16
	v_lshlrev_b32_e32 v8, 7, v71
	v_bfe_u32 v9, v71, 16, 16
	v_and_or_b32 v0, v0, s68, v150
	v_lshl_or_b32 v4, v1, 7, v150
	v_and_or_b32 v8, v8, s68, v150
	v_lshl_or_b32 v12, v9, 7, v150
	s_lshl_b32 s40, s33, 11
	global_load_dwordx4 v[0:3], v0, s[50:51]
	s_nop 0
	global_load_dwordx4 v[4:7], v4, s[50:51]
	s_nop 0
	global_load_dwordx4 v[8:11], v8, s[50:51]
	s_nop 0
	global_load_dwordx4 v[16:19], v12, s[50:51]
	v_lshl_add_u64 v[12:13], v[166:167], 0, s[40:41]
	s_lshl_b32 s40, s45, 8
	v_lshl_add_u64 v[12:13], v[12:13], 0, s[40:41]
	global_load_dword v220, v[12:13], off
	v_lshl_add_u32 v12, s33, 7, v187
	s_and_b32 s33, s0, 0x780
	v_lshl_add_u32 v68, s33, 1, v185
	ds_read_b128 v[12:15], v12
	ds_read_b128 v[72:75], v68
	ds_read_b128 v[68:71], v68 offset:16
	s_waitcnt vmcnt(33)
	v_perm_b32 v145, v132, v128, s71
	v_perm_b32 v128, v132, v128, s72
	s_waitcnt vmcnt(31)
	v_perm_b32 v132, v140, v136, s71
	v_perm_b32 v136, v140, v136, s72
	v_perm_b32 v140, v132, v145, s73
	v_perm_b32 v132, v132, v145, s74
	v_mov_b32_e32 v145, 0
	v_dot4c_i32_i8_e32 v145, v132, v92
	v_perm_b32 v132, v136, v128, s73
	v_perm_b32 v128, v136, v128, s74
	v_dot4_i32_i8 v146, v132, v92, 0
	v_dot4_i32_i8 v147, v128, v92, 0
	v_perm_b32 v128, v133, v129, s71
	v_perm_b32 v132, v141, v137, s71
	v_perm_b32 v129, v133, v129, s72
	v_perm_b32 v133, v141, v137, s72
	v_perm_b32 v136, v132, v128, s73
	v_perm_b32 v128, v132, v128, s74
	v_dot4_i32_i8 v223, v128, v92, 0
	v_perm_b32 v128, v133, v129, s73
	v_dot4_i32_i8 v224, v128, v92, 0
	v_perm_b32 v128, v133, v129, s74
	v_dot4_i32_i8 v225, v128, v92, 0
	v_perm_b32 v128, v134, v130, s71
	v_perm_b32 v129, v134, v130, s72
	v_perm_b32 v130, v142, v138, s71
	v_perm_b32 v132, v142, v138, s72
	v_perm_b32 v133, v130, v128, s73
	v_perm_b32 v128, v130, v128, s74
	v_dot4_i32_i8 v227, v128, v92, 0
	v_perm_b32 v128, v132, v129, s73
	v_dot4_i32_i8 v228, v128, v92, 0
	v_perm_b32 v128, v132, v129, s74
	v_perm_b32 v129, v135, v131, s71
	v_perm_b32 v130, v143, v139, s71
	v_dot4_i32_i8 v226, v133, v92, 0
	v_dot4_i32_i8 v229, v128, v92, 0
	v_perm_b32 v131, v135, v131, s72
	v_perm_b32 v132, v143, v139, s72
	v_perm_b32 v133, v130, v129, s73
	v_perm_b32 v130, v130, v129, s74
	v_mov_b32_e32 v129, 0
	v_dot4_i32_i8 v128, v133, v92, 0
	v_dot4c_i32_i8_e32 v129, v130, v92
	v_perm_b32 v133, v132, v131, s73
	v_mov_b32_e32 v130, 0
	v_perm_b32 v132, v132, v131, s74
	v_mov_b32_e32 v131, 0
	v_dot4_i32_i8 v144, v140, v92, 0
	v_dot4_i32_i8 v222, v136, v92, 0
	v_dot4c_i32_i8_e32 v130, v133, v92
	v_dot4c_i32_i8_e32 v131, v132, v92
	s_waitcnt vmcnt(29)
	v_perm_b32 v92, v116, v112, s71
	v_perm_b32 v112, v116, v112, s72
	s_waitcnt vmcnt(27)
	v_perm_b32 v116, v124, v120, s71
	v_perm_b32 v120, v124, v120, s72
	v_perm_b32 v124, v116, v92, s73
	v_perm_b32 v92, v116, v92, s74
	v_dot4c_i32_i8_e32 v145, v92, v93
	v_perm_b32 v92, v120, v112, s73
	v_dot4c_i32_i8_e32 v146, v92, v93
	v_perm_b32 v92, v120, v112, s74
	v_dot4c_i32_i8_e32 v147, v92, v93
	v_perm_b32 v92, v117, v113, s71
	v_perm_b32 v112, v117, v113, s72
	v_perm_b32 v113, v125, v121, s71
	v_perm_b32 v116, v125, v121, s72
	v_perm_b32 v117, v113, v92, s73
	v_perm_b32 v92, v113, v92, s74
	v_dot4c_i32_i8_e32 v223, v92, v93
	v_perm_b32 v92, v116, v112, s73
	v_dot4c_i32_i8_e32 v224, v92, v93
	v_perm_b32 v92, v116, v112, s74
	v_dot4c_i32_i8_e32 v225, v92, v93
	v_perm_b32 v92, v118, v114, s71
	v_perm_b32 v113, v126, v122, s71
	v_perm_b32 v112, v118, v114, s72
	v_perm_b32 v114, v126, v122, s72
	v_perm_b32 v116, v113, v92, s73
	v_perm_b32 v92, v113, v92, s74
	v_dot4c_i32_i8_e32 v227, v92, v93
	v_perm_b32 v92, v114, v112, s73
	v_dot4c_i32_i8_e32 v228, v92, v93
	v_perm_b32 v92, v114, v112, s74
	v_dot4c_i32_i8_e32 v229, v92, v93
	v_perm_b32 v92, v119, v115, s71
	v_perm_b32 v113, v127, v123, s71
	v_perm_b32 v112, v119, v115, s72
	v_perm_b32 v114, v127, v123, s72
	v_perm_b32 v115, v113, v92, s73
	v_perm_b32 v92, v113, v92, s74
	v_dot4c_i32_i8_e32 v129, v92, v93
	v_perm_b32 v92, v114, v112, s73
	v_dot4c_i32_i8_e32 v130, v92, v93
	v_perm_b32 v92, v114, v112, s74
	v_dot4c_i32_i8_e32 v144, v124, v93
	v_dot4c_i32_i8_e32 v222, v117, v93
	v_dot4c_i32_i8_e32 v226, v116, v93
	v_dot4c_i32_i8_e32 v128, v115, v93
	v_dot4c_i32_i8_e32 v131, v92, v93
	s_waitcnt vmcnt(25)
	v_perm_b32 v92, v100, v96, s71
	v_perm_b32 v93, v100, v96, s72
	s_waitcnt vmcnt(23)
	v_perm_b32 v96, v108, v104, s71
	v_perm_b32 v100, v108, v104, s72
	v_perm_b32 v104, v96, v92, s73
	v_perm_b32 v92, v96, v92, s74
	v_dot4c_i32_i8_e32 v145, v92, v94
	v_perm_b32 v92, v100, v93, s73
	v_dot4c_i32_i8_e32 v146, v92, v94
	v_perm_b32 v92, v100, v93, s74
	v_dot4c_i32_i8_e32 v147, v92, v94
	v_perm_b32 v92, v101, v97, s71
	v_perm_b32 v96, v109, v105, s71
	v_perm_b32 v93, v101, v97, s72
	v_perm_b32 v97, v109, v105, s72
	v_perm_b32 v100, v96, v92, s73
	v_perm_b32 v92, v96, v92, s74
	v_dot4c_i32_i8_e32 v223, v92, v94
	v_perm_b32 v92, v97, v93, s73
	v_dot4c_i32_i8_e32 v224, v92, v94
	v_perm_b32 v92, v97, v93, s74
	v_dot4c_i32_i8_e32 v225, v92, v94
	v_perm_b32 v92, v102, v98, s71
	v_perm_b32 v96, v110, v106, s71
	v_perm_b32 v93, v102, v98, s72
	v_perm_b32 v97, v110, v106, s72
	v_perm_b32 v98, v96, v92, s73
	v_perm_b32 v92, v96, v92, s74
	v_dot4c_i32_i8_e32 v227, v92, v94
	v_perm_b32 v92, v97, v93, s73
	v_dot4c_i32_i8_e32 v228, v92, v94
	v_perm_b32 v92, v97, v93, s74
	v_dot4c_i32_i8_e32 v229, v92, v94
	v_perm_b32 v92, v103, v99, s71
	v_perm_b32 v96, v111, v107, s71
	v_dot4c_i32_i8_e32 v226, v98, v94
	v_perm_b32 v93, v103, v99, s72
	v_perm_b32 v97, v111, v107, s72
	v_perm_b32 v98, v96, v92, s73
	v_perm_b32 v92, v96, v92, s74
	v_dot4c_i32_i8_e32 v129, v92, v94
	v_perm_b32 v92, v97, v93, s73
	v_dot4c_i32_i8_e32 v130, v92, v94
	v_perm_b32 v92, v97, v93, s74
	v_dot4c_i32_i8_e32 v131, v92, v94
	s_waitcnt vmcnt(21)
	v_perm_b32 v92, v80, v76, s71
	v_perm_b32 v76, v80, v76, s72
	s_waitcnt vmcnt(19)
	v_perm_b32 v80, v88, v84, s71
	v_perm_b32 v84, v88, v84, s72
	v_perm_b32 v88, v80, v92, s73
	v_perm_b32 v80, v80, v92, s74
	v_dot4c_i32_i8_e32 v145, v80, v95
	v_perm_b32 v80, v84, v76, s73
	v_perm_b32 v76, v84, v76, s74
	v_dot4c_i32_i8_e32 v146, v80, v95
	v_dot4c_i32_i8_e32 v147, v76, v95
	v_perm_b32 v76, v81, v77, s71
	v_perm_b32 v80, v89, v85, s71
	v_perm_b32 v77, v81, v77, s72
	v_perm_b32 v81, v89, v85, s72
	v_perm_b32 v84, v80, v76, s73
	v_perm_b32 v76, v80, v76, s74
	v_dot4c_i32_i8_e32 v223, v76, v95
	v_perm_b32 v76, v81, v77, s73
	v_dot4c_i32_i8_e32 v224, v76, v95
	v_perm_b32 v76, v81, v77, s74
	v_dot4c_i32_i8_e32 v225, v76, v95
	v_perm_b32 v76, v82, v78, s71
	v_perm_b32 v77, v82, v78, s72
	v_perm_b32 v78, v90, v86, s71
	v_perm_b32 v80, v90, v86, s72
	v_perm_b32 v81, v78, v76, s73
	v_perm_b32 v76, v78, v76, s74
	v_dot4c_i32_i8_e32 v227, v76, v95
	v_perm_b32 v76, v80, v77, s73
	v_dot4c_i32_i8_e32 v228, v76, v95
	v_perm_b32 v76, v80, v77, s74
	v_dot4c_i32_i8_e32 v229, v76, v95
	v_perm_b32 v76, v83, v79, s71
	v_perm_b32 v78, v91, v87, s71
	v_perm_b32 v77, v83, v79, s72
	v_perm_b32 v79, v91, v87, s72
	v_perm_b32 v80, v78, v76, s73
	v_perm_b32 v76, v78, v76, s74
	v_dot4c_i32_i8_e32 v144, v104, v94
	v_dot4c_i32_i8_e32 v129, v76, v95
	v_perm_b32 v76, v79, v77, s73
	v_dot4c_i32_i8_e32 v222, v100, v94
	v_dot4c_i32_i8_e32 v128, v98, v94
	v_dot4c_i32_i8_e32 v144, v88, v95
	v_dot4c_i32_i8_e32 v130, v76, v95
	v_perm_b32 v76, v79, v77, s74
	v_dot4c_i32_i8_e32 v222, v84, v95
	v_dot4c_i32_i8_e32 v226, v81, v95
	v_dot4c_i32_i8_e32 v128, v80, v95
	v_dot4c_i32_i8_e32 v131, v76, v95
	ds_write_b128 v219, v[144:147] offset:2048
	ds_write_b128 v219, v[222:225] offset:2064
	ds_write_b128 v219, v[226:229] offset:2080
	ds_write_b128 v219, v[128:131] offset:2096
	ds_read2st64_b64 v[76:79], v188 offset0:4 offset1:5
	ds_read2st64_b64 v[80:83], v188 offset0:6 offset1:7
	ds_read2st64_b64 v[84:87], v188 offset0:8 offset1:9
	ds_read2st64_b64 v[88:91], v188 offset0:10 offset1:11
	ds_read_b32 v92, v230 offset:4
	s_waitcnt lgkmcnt(4)
	v_add_u32_e32 v77, v79, v77
	v_add_u32_e32 v76, v78, v76
	s_waitcnt lgkmcnt(3)
	v_add3_u32 v76, v76, v80, v82
	v_add3_u32 v77, v77, v81, v83
	s_waitcnt lgkmcnt(2)
	v_add3_u32 v77, v77, v85, v87
	v_add3_u32 v76, v76, v84, v86
	s_waitcnt lgkmcnt(1)
	v_add3_u32 v76, v76, v88, v90
	v_add3_u32 v77, v77, v89, v91
	v_cvt_f32_i32_e32 v77, v77
	v_cvt_f32_i32_e32 v76, v76
	s_waitcnt vmcnt(18)
	v_lshlrev_b32_e32 v78, 16, v221
	v_and_b32_e32 v79, 0xffff0000, v221
	s_waitcnt lgkmcnt(0)
	v_pk_fma_f32 v[76:77], v[92:93], v[76:77], v[78:79] op_sel_hi:[0,1,1]
	v_cvt_pk_bf16_f32 v76, v76, v77
	global_store_dword v[168:169], v76, off
	s_addk_i32 s0, 0x100
	s_cmpk_gt_u32 s1, 0x6d
	s_mov_b32 s33, s1
	s_cbranch_scc0 .LBB0_1394
	global_load_dword v228, v[166:167], off sc1
	global_load_dword v227, v[166:167], off offset:256 sc1
	global_load_dword v226, v[166:167], off offset:512 sc1
	global_load_dword v225, v[166:167], off offset:768 sc1
	global_load_dword v224, v[166:167], off offset:1024 sc1
	global_load_dword v223, v[166:167], off offset:1280 sc1
	global_load_dword v222, v[166:167], off offset:1536 sc1
	s_ashr_i32 s45, s44, 31
	s_lshl_b64 s[0:1], s[44:45], 11
	v_lshl_add_u64 v[168:169], v[164:165], 0, s[0:1]
	s_mov_b32 s76, 0
	v_mov_b32_e32 v221, v207
	s_mov_b32 s33, s66
.LBB0_1396:
	v_lshlrev_b32_e32 v76, 7, v72
	v_bfe_u32 v72, v72, 16, 16
	v_and_or_b32 v76, v76, s68, v150
	v_lshl_or_b32 v72, v72, 7, v150
	global_load_dwordx4 v[128:131], v76, s[42:43]
	global_load_dwordx4 v[132:135], v72, s[42:43]
	v_lshlrev_b32_e32 v72, 7, v73
	v_and_or_b32 v72, v72, s68, v150
	v_bfe_u32 v73, v73, 16, 16
	v_lshl_or_b32 v73, v73, 7, v150
	global_load_dwordx4 v[136:139], v72, s[42:43]
	global_load_dwordx4 v[140:143], v73, s[42:43]
	v_lshlrev_b32_e32 v72, 7, v74
	v_and_or_b32 v72, v72, s68, v150
	v_bfe_u32 v73, v74, 16, 16
	v_lshl_or_b32 v73, v73, 7, v150
	global_load_dwordx4 v[112:115], v72, s[42:43]
	global_load_dwordx4 v[116:119], v73, s[42:43]
	v_lshlrev_b32_e32 v72, 7, v75
	v_and_or_b32 v72, v72, s68, v150
	v_bfe_u32 v73, v75, 16, 16
	v_lshl_or_b32 v73, v73, 7, v150
	global_load_dwordx4 v[120:123], v72, s[42:43]
	global_load_dwordx4 v[124:127], v73, s[42:43]
	v_lshlrev_b32_e32 v72, 7, v68
	v_bfe_u32 v68, v68, 16, 16
	v_and_or_b32 v72, v72, s68, v150
	v_lshl_or_b32 v68, v68, 7, v150
	global_load_dwordx4 v[96:99], v72, s[42:43]
	global_load_dwordx4 v[100:103], v68, s[42:43]
	v_lshlrev_b32_e32 v68, 7, v69
	v_and_or_b32 v68, v68, s68, v150
	v_bfe_u32 v69, v69, 16, 16
	v_lshl_or_b32 v69, v69, 7, v150
	global_load_dwordx4 v[104:107], v68, s[42:43]
	global_load_dwordx4 v[108:111], v69, s[42:43]
	v_lshlrev_b32_e32 v68, 7, v70
	v_and_or_b32 v68, v68, s68, v150
	v_bfe_u32 v69, v70, 16, 16
	v_lshl_or_b32 v69, v69, 7, v150
	global_load_dwordx4 v[80:83], v68, s[42:43]
	global_load_dwordx4 v[84:87], v69, s[42:43]
	v_lshlrev_b32_e32 v68, 7, v71
	v_and_or_b32 v68, v68, s68, v150
	v_bfe_u32 v69, v71, 16, 16
	v_lshl_or_b32 v69, v69, 7, v150
	global_load_dwordx4 v[88:91], v68, s[42:43]
	global_load_dwordx4 v[92:95], v69, s[42:43]
	ds_read_b128 v[76:79], v221
	global_load_dword v236, v[168:169], off offset:1792
	global_load_dword v235, v[168:169], off sc1
	global_load_dword v234, v[168:169], off offset:256 sc1
	global_load_dword v233, v[168:169], off offset:512 sc1
	global_load_dword v232, v[168:169], off offset:768 sc1
	global_load_dword v231, v[168:169], off offset:1024 sc1
	global_load_dword v230, v[168:169], off offset:1280 sc1
	global_load_dword v229, v[168:169], off offset:1536 sc1
	s_add_i32 s45, s76, 2
	s_cmp_lt_u32 s76, 14
	s_cselect_b32 s52, s45, 15
	v_lshl_add_u32 v68, s52, 8, v185
	s_add_i32 s0, s44, s76
	ds_read_b128 v[72:75], v68
	ds_read_b128 v[68:71], v68 offset:16
	s_ashr_i32 s1, s0, 31
	s_lshl_b64 s[48:49], s[0:1], 12
	s_add_i32 s0, s0, 1
	s_ashr_i32 s1, s0, 31
	s_add_i32 s53, s33, -4
	s_lshl_b32 s40, s52, 11
	s_min_u32 s51, s76, 12
	s_lshl_b64 s[0:1], s[0:1], 12
	s_add_i32 s50, s33, 8
	s_cmp_gt_u32 s76, 13
	s_waitcnt vmcnt(47)
	v_perm_b32 v145, v52, v64, s71
	v_perm_b32 v52, v52, v64, s72
	s_waitcnt vmcnt(45)
	v_perm_b32 v64, v60, v56, s71
	v_perm_b32 v56, v60, v56, s72
	v_perm_b32 v60, v64, v145, s73
	v_dot4_i32_i8 v144, v60, v12, 0
	v_perm_b32 v60, v64, v145, s74
	v_mov_b32_e32 v145, 0
	v_dot4c_i32_i8_e32 v145, v60, v12
	v_perm_b32 v60, v56, v52, s73
	v_perm_b32 v52, v56, v52, s74
	v_dot4_i32_i8 v147, v52, v12, 0
	v_perm_b32 v52, v53, v65, s71
	v_perm_b32 v56, v61, v57, s71
	v_dot4_i32_i8 v146, v60, v12, 0
	v_perm_b32 v53, v53, v65, s72
	v_perm_b32 v57, v61, v57, s72
	v_perm_b32 v60, v56, v52, s73
	v_perm_b32 v52, v56, v52, s74
	v_dot4_i32_i8 v239, v52, v12, 0
	v_perm_b32 v52, v57, v53, s73
	v_dot4_i32_i8 v240, v52, v12, 0
	v_perm_b32 v52, v57, v53, s74
	v_dot4_i32_i8 v241, v52, v12, 0
	v_perm_b32 v52, v54, v66, s71
	v_perm_b32 v53, v54, v66, s72
	v_perm_b32 v54, v62, v58, s71
	v_perm_b32 v56, v62, v58, s72
	v_perm_b32 v57, v54, v52, s73
	v_perm_b32 v52, v54, v52, s74
	v_dot4_i32_i8 v243, v52, v12, 0
	v_perm_b32 v52, v56, v53, s73
	v_dot4_i32_i8 v244, v52, v12, 0
	v_perm_b32 v52, v56, v53, s74
	v_perm_b32 v53, v55, v67, s71
	v_perm_b32 v54, v63, v59, s71
	v_dot4_i32_i8 v242, v57, v12, 0
	v_dot4_i32_i8 v245, v52, v12, 0
	v_perm_b32 v55, v55, v67, s72
	v_perm_b32 v56, v63, v59, s72
	v_perm_b32 v57, v54, v53, s73
	v_perm_b32 v54, v54, v53, s74
	v_mov_b32_e32 v53, 0
	v_dot4_i32_i8 v52, v57, v12, 0
	v_dot4c_i32_i8_e32 v53, v54, v12
	v_perm_b32 v57, v56, v55, s73
	v_mov_b32_e32 v54, 0
	v_perm_b32 v56, v56, v55, s74
	v_mov_b32_e32 v55, 0
	v_dot4_i32_i8 v238, v60, v12, 0
	v_dot4c_i32_i8_e32 v54, v57, v12
	v_dot4c_i32_i8_e32 v55, v56, v12
	s_waitcnt vmcnt(43)
	v_perm_b32 v12, v40, v36, s71
	v_perm_b32 v36, v40, v36, s72
	s_waitcnt vmcnt(41)
	v_perm_b32 v40, v48, v44, s71
	v_perm_b32 v44, v48, v44, s72
	v_perm_b32 v48, v40, v12, s73
	v_perm_b32 v12, v40, v12, s74
	v_dot4c_i32_i8_e32 v145, v12, v13
	v_perm_b32 v12, v44, v36, s73
	v_dot4c_i32_i8_e32 v146, v12, v13
	v_perm_b32 v12, v44, v36, s74
	v_dot4c_i32_i8_e32 v147, v12, v13
	v_perm_b32 v12, v41, v37, s71
	v_perm_b32 v36, v41, v37, s72
	v_perm_b32 v37, v49, v45, s71
	v_perm_b32 v40, v49, v45, s72
	v_perm_b32 v41, v37, v12, s73
	v_perm_b32 v12, v37, v12, s74
	v_dot4c_i32_i8_e32 v239, v12, v13
	v_perm_b32 v12, v40, v36, s73
	v_dot4c_i32_i8_e32 v240, v12, v13
	v_perm_b32 v12, v40, v36, s74
	v_dot4c_i32_i8_e32 v241, v12, v13
	v_perm_b32 v12, v42, v38, s71
	v_perm_b32 v37, v50, v46, s71
	v_perm_b32 v36, v42, v38, s72
	v_perm_b32 v38, v50, v46, s72
	v_perm_b32 v40, v37, v12, s73
	v_perm_b32 v12, v37, v12, s74
	v_dot4c_i32_i8_e32 v243, v12, v13
	v_perm_b32 v12, v38, v36, s73
	v_dot4c_i32_i8_e32 v244, v12, v13
	v_perm_b32 v12, v38, v36, s74
	v_dot4c_i32_i8_e32 v245, v12, v13
	v_perm_b32 v12, v43, v39, s71
	v_perm_b32 v37, v51, v47, s71
	v_perm_b32 v36, v43, v39, s72
	v_perm_b32 v38, v51, v47, s72
	v_perm_b32 v39, v37, v12, s73
	v_perm_b32 v12, v37, v12, s74
	v_dot4c_i32_i8_e32 v53, v12, v13
	v_perm_b32 v12, v38, v36, s73
	v_dot4c_i32_i8_e32 v54, v12, v13
	v_perm_b32 v12, v38, v36, s74
	v_dot4c_i32_i8_e32 v144, v48, v13
	v_dot4c_i32_i8_e32 v238, v41, v13
	v_dot4c_i32_i8_e32 v242, v40, v13
	v_dot4c_i32_i8_e32 v52, v39, v13
	v_dot4c_i32_i8_e32 v55, v12, v13
	s_waitcnt vmcnt(39)
	v_perm_b32 v12, v24, v20, s71
	v_perm_b32 v13, v24, v20, s72
	s_waitcnt vmcnt(37)
	v_perm_b32 v20, v32, v28, s71
	v_perm_b32 v24, v32, v28, s72
	v_perm_b32 v28, v20, v12, s73
	v_perm_b32 v12, v20, v12, s74
	v_dot4c_i32_i8_e32 v145, v12, v14
	v_perm_b32 v12, v24, v13, s73
	v_dot4c_i32_i8_e32 v146, v12, v14
	v_perm_b32 v12, v24, v13, s74
	v_dot4c_i32_i8_e32 v147, v12, v14
	v_perm_b32 v12, v25, v21, s71
	v_perm_b32 v20, v33, v29, s71
	v_perm_b32 v13, v25, v21, s72
	v_perm_b32 v21, v33, v29, s72
	v_perm_b32 v24, v20, v12, s73
	v_perm_b32 v12, v20, v12, s74
	v_dot4c_i32_i8_e32 v239, v12, v14
	v_perm_b32 v12, v21, v13, s73
	v_dot4c_i32_i8_e32 v240, v12, v14
	v_perm_b32 v12, v21, v13, s74
	v_dot4c_i32_i8_e32 v241, v12, v14
	v_perm_b32 v12, v26, v22, s71
	v_perm_b32 v20, v34, v30, s71
	v_perm_b32 v13, v26, v22, s72
	v_perm_b32 v21, v34, v30, s72
	v_perm_b32 v22, v20, v12, s73
	v_perm_b32 v12, v20, v12, s74
	v_dot4c_i32_i8_e32 v243, v12, v14
	v_perm_b32 v12, v21, v13, s73
	v_dot4c_i32_i8_e32 v244, v12, v14
	v_perm_b32 v12, v21, v13, s74
	v_dot4c_i32_i8_e32 v245, v12, v14
	v_perm_b32 v12, v27, v23, s71
	v_perm_b32 v20, v35, v31, s71
	v_dot4c_i32_i8_e32 v242, v22, v14
	v_perm_b32 v13, v27, v23, s72
	v_perm_b32 v21, v35, v31, s72
	v_perm_b32 v22, v20, v12, s73
	v_perm_b32 v12, v20, v12, s74
	v_dot4c_i32_i8_e32 v53, v12, v14
	v_perm_b32 v12, v21, v13, s73
	v_dot4c_i32_i8_e32 v54, v12, v14
	v_perm_b32 v12, v21, v13, s74
	v_dot4c_i32_i8_e32 v55, v12, v14
	s_waitcnt vmcnt(35)
	v_perm_b32 v12, v4, v0, s71
	v_perm_b32 v0, v4, v0, s72
	s_waitcnt vmcnt(33)
	v_perm_b32 v4, v16, v8, s71
	v_perm_b32 v8, v16, v8, s72
	v_perm_b32 v13, v4, v12, s73
	v_perm_b32 v4, v4, v12, s74
	v_dot4c_i32_i8_e32 v145, v4, v15
	v_perm_b32 v4, v8, v0, s73
	v_perm_b32 v0, v8, v0, s74
	v_dot4c_i32_i8_e32 v146, v4, v15
	v_dot4c_i32_i8_e32 v147, v0, v15
	v_perm_b32 v0, v5, v1, s71
	v_perm_b32 v4, v17, v9, s71
	v_perm_b32 v1, v5, v1, s72
	v_perm_b32 v5, v17, v9, s72
	v_perm_b32 v8, v4, v0, s73
	v_perm_b32 v0, v4, v0, s74
	v_dot4c_i32_i8_e32 v239, v0, v15
	v_perm_b32 v0, v5, v1, s73
	v_dot4c_i32_i8_e32 v240, v0, v15
	v_perm_b32 v0, v5, v1, s74
	v_dot4c_i32_i8_e32 v241, v0, v15
	v_perm_b32 v0, v6, v2, s71
	v_perm_b32 v1, v6, v2, s72
	v_perm_b32 v2, v18, v10, s71
	v_perm_b32 v4, v18, v10, s72
	v_perm_b32 v5, v2, v0, s73
	v_perm_b32 v0, v2, v0, s74
	v_dot4c_i32_i8_e32 v243, v0, v15
	v_perm_b32 v0, v4, v1, s73
	v_dot4c_i32_i8_e32 v244, v0, v15
	v_perm_b32 v0, v4, v1, s74
	v_dot4c_i32_i8_e32 v245, v0, v15
	v_perm_b32 v0, v7, v3, s71
	v_perm_b32 v2, v19, v11, s71
	v_perm_b32 v1, v7, v3, s72
	v_perm_b32 v3, v19, v11, s72
	v_perm_b32 v4, v2, v0, s73
	v_perm_b32 v0, v2, v0, s74
	v_dot4c_i32_i8_e32 v144, v28, v14
	v_dot4c_i32_i8_e32 v53, v0, v15
	v_perm_b32 v0, v3, v1, s73
	v_dot4c_i32_i8_e32 v238, v24, v14
	v_dot4c_i32_i8_e32 v52, v22, v14
	v_dot4c_i32_i8_e32 v144, v13, v15
	v_dot4c_i32_i8_e32 v54, v0, v15
	v_perm_b32 v0, v3, v1, s74
	v_dot4c_i32_i8_e32 v238, v8, v15
	v_dot4c_i32_i8_e32 v242, v5, v15
	v_dot4c_i32_i8_e32 v52, v4, v15
	v_dot4c_i32_i8_e32 v55, v0, v15
	ds_write_b128 v219, v[144:147] offset:2048
	ds_write_b128 v219, v[238:241] offset:2064
	ds_write_b128 v219, v[242:245] offset:2080
	ds_write_b128 v219, v[52:55] offset:2096
	ds_read2st64_b64 v[0:3], v188 offset0:4 offset1:5
	ds_read2st64_b64 v[4:7], v188 offset0:6 offset1:7
	s_waitcnt vmcnt(30)
	v_lshlrev_b32_e32 v16, 16, v228
	v_and_b32_e32 v17, 0xffff0000, v228
	s_waitcnt vmcnt(29)
	v_lshlrev_b32_e32 v18, 16, v227
	s_waitcnt lgkmcnt(1)
	v_add_u32_e32 v13, v2, v0
	v_add_u32_e32 v40, v3, v1
	ds_read2st64_b64 v[0:3], v188 offset0:8 offset1:9
	ds_read2st64_b64 v[8:11], v188 offset0:10 offset1:11
	global_load_dwordx2 v[30:31], v[162:163], off
	s_waitcnt lgkmcnt(2)
	v_add3_u32 v4, v13, v4, v6
	v_and_b32_e32 v19, 0xffff0000, v227
	v_pk_mul_f32 v[32:33], v[16:17], v[16:17]
	s_waitcnt lgkmcnt(1)
	v_add3_u32 v0, v4, v0, v2
	v_pk_mul_f32 v[34:35], v[18:19], v[18:19]
	s_waitcnt lgkmcnt(0)
	v_add3_u32 v0, v0, v8, v10
	v_add_f32_e32 v10, v32, v33
	s_waitcnt vmcnt(29)
	v_lshlrev_b32_e32 v20, 16, v226
	v_and_b32_e32 v21, 0xffff0000, v226
	v_add_f32_e32 v10, v34, v10
	v_pk_mul_f32 v[36:37], v[20:21], v[20:21]
	v_add_f32_e32 v10, v35, v10
	s_waitcnt vmcnt(28)
	v_lshlrev_b32_e32 v22, 16, v225
	v_and_b32_e32 v23, 0xffff0000, v225
	v_add_f32_e32 v10, v36, v10
	v_pk_mul_f32 v[38:39], v[22:23], v[22:23]
	v_add3_u32 v5, v40, v5, v7
	v_add_f32_e32 v10, v37, v10
	v_mov_b32_e32 v12, s53
	s_waitcnt vmcnt(27)
	v_lshlrev_b32_e32 v24, 16, v224
	v_and_b32_e32 v25, 0xffff0000, v224
	v_add3_u32 v1, v5, v1, v3
	v_add_f32_e32 v10, v38, v10
	ds_read_b32 v12, v12
	v_add3_u32 v1, v1, v9, v11
	v_pk_mul_f32 v[2:3], v[24:25], v[24:25]
	v_add_f32_e32 v10, v39, v10
	s_waitcnt vmcnt(26)
	v_lshlrev_b32_e32 v26, 16, v223
	v_and_b32_e32 v27, 0xffff0000, v223
	v_cvt_f32_i32_e32 v1, v1
	v_cvt_f32_i32_e32 v0, v0
	v_add_f32_e32 v2, v2, v10
	v_pk_mul_f32 v[4:5], v[26:27], v[26:27]
	v_add_f32_e32 v2, v3, v2
	s_waitcnt vmcnt(25)
	global_load_dwordx2 v[42:43], v[162:163], off offset:512
	global_load_dwordx2 v[44:45], v[162:163], off offset:1024
	global_load_dwordx2 v[46:47], v[162:163], off offset:1536
	global_load_dwordx2 v[48:49], v[162:163], off offset:2048
	global_load_dwordx2 v[50:51], v[162:163], off offset:2560
	global_load_dwordx2 v[56:57], v[162:163], off offset:3072
	global_load_dwordx2 v[58:59], v[162:163], off offset:3584
	v_lshlrev_b32_e32 v28, 16, v222
	v_and_b32_e32 v29, 0xffff0000, v222
	v_add_f32_e32 v2, v4, v2
	v_lshlrev_b32_e32 v14, 16, v220
	v_and_b32_e32 v15, 0xffff0000, v220
	v_pk_mul_f32 v[6:7], v[28:29], v[28:29]
	v_add_f32_e32 v2, v5, v2
	s_waitcnt lgkmcnt(0)
	v_pk_fma_f32 v[0:1], v[12:13], v[0:1], v[14:15] op_sel_hi:[0,1,1]
	v_add_f32_e32 v2, v6, v2
	v_pk_mul_f32 v[8:9], v[0:1], v[0:1]
	v_add_f32_e32 v2, v7, v2
	v_add_f32_e32 v2, v2, v8
	v_add_f32_e32 v2, v9, v2
	ds_bpermute_b32 v3, v189, v2
	s_waitcnt lgkmcnt(0)
	v_add_f32_e32 v2, v2, v3
	ds_bpermute_b32 v3, v190, v2
	s_waitcnt lgkmcnt(0)
	v_add_f32_e32 v2, v2, v3
	ds_bpermute_b32 v3, v191, v2
	s_waitcnt lgkmcnt(0)
	v_add_f32_e32 v2, v2, v3
	ds_bpermute_b32 v3, v192, v2
	s_waitcnt lgkmcnt(0)
	v_add_f32_e32 v2, v2, v3
	ds_bpermute_b32 v3, v193, v2
	s_waitcnt lgkmcnt(0)
	v_add_f32_e32 v2, v2, v3
	ds_bpermute_b32 v3, v194, v2
	s_waitcnt lgkmcnt(0)
	v_add_f32_e32 v2, v2, v3
	v_fmamk_f32 v2, v2, 0x3a800000, v216
	v_mul_f32_e32 v3, 0x4b800000, v2
	v_cmp_gt_f32_e32 vcc, s75, v2
	s_nop 1
	v_cndmask_b32_e32 v2, v2, v3, vcc
	v_rsq_f32_e32 v4, v2
	v_lshl_add_u64 v[2:3], v[160:161], 0, s[48:49]
	v_mul_f32_e32 v5, 0x45800000, v4
	v_cndmask_b32_e32 v4, v4, v5, vcc
	v_pk_mul_f32 v[6:7], v[4:5], v[16:17] op_sel_hi:[0,1]
	s_waitcnt vmcnt(0)
	v_pk_mul_f32 v[6:7], v[30:31], v[6:7]
	global_store_dwordx2 v[2:3], v[6:7], off nt
	v_pk_mul_f32 v[8:9], v[4:5], v[18:19] op_sel_hi:[0,1]
	v_pk_mul_f32 v[0:1], v[0:1], v[4:5] op_sel_hi:[1,0]
	s_nop 0
	v_pk_mul_f32 v[6:7], v[42:43], v[8:9]
	global_store_dwordx2 v[2:3], v[6:7], off offset:512 nt
	v_pk_mul_f32 v[8:9], v[4:5], v[20:21] op_sel_hi:[0,1]
	s_nop 0
	v_pk_mul_f32 v[6:7], v[44:45], v[8:9]
	global_store_dwordx2 v[2:3], v[6:7], off offset:1024 nt
	v_pk_mul_f32 v[8:9], v[4:5], v[22:23] op_sel_hi:[0,1]
	s_nop 0
	v_pk_mul_f32 v[6:7], v[46:47], v[8:9]
	global_store_dwordx2 v[2:3], v[6:7], off offset:1536 nt
	v_pk_mul_f32 v[8:9], v[4:5], v[24:25] op_sel_hi:[0,1]
	s_nop 0
	v_pk_mul_f32 v[6:7], v[48:49], v[8:9]
	global_store_dwordx2 v[2:3], v[6:7], off offset:2048 nt
	v_pk_mul_f32 v[8:9], v[4:5], v[26:27] op_sel_hi:[0,1]
	s_nop 0
	v_pk_mul_f32 v[6:7], v[50:51], v[8:9]
	global_store_dwordx2 v[2:3], v[6:7], off offset:2560 nt
	v_pk_mul_f32 v[8:9], v[4:5], v[28:29] op_sel_hi:[0,1]
	s_nop 0
	v_pk_mul_f32 v[6:7], v[56:57], v[8:9]
	global_store_dwordx2 v[2:3], v[6:7], off offset:3072 nt
	s_nop 0
	v_pk_mul_f32 v[0:1], v[0:1], v[58:59]
	global_store_dwordx2 v[2:3], v[0:1], off offset:3584 nt
	v_lshlrev_b32_e32 v0, 7, v72
	v_bfe_u32 v1, v72, 16, 16
	v_and_or_b32 v0, v0, s68, v150
	v_lshl_or_b32 v1, v1, 7, v150
	global_load_dwordx4 v[64:67], v0, s[42:43]
	global_load_dwordx4 v[52:55], v1, s[42:43]
	v_lshlrev_b32_e32 v0, 7, v73
	v_bfe_u32 v1, v73, 16, 16
	v_and_or_b32 v0, v0, s68, v150
	v_lshl_or_b32 v1, v1, 7, v150
	global_load_dwordx4 v[56:59], v0, s[42:43]
	global_load_dwordx4 v[60:63], v1, s[42:43]
	v_lshlrev_b32_e32 v0, 7, v74
	v_bfe_u32 v1, v74, 16, 16
	v_and_or_b32 v0, v0, s68, v150
	v_lshl_or_b32 v1, v1, 7, v150
	global_load_dwordx4 v[36:39], v0, s[42:43]
	global_load_dwordx4 v[40:43], v1, s[42:43]
	v_lshlrev_b32_e32 v0, 7, v75
	v_bfe_u32 v1, v75, 16, 16
	v_and_or_b32 v0, v0, s68, v150
	v_lshl_or_b32 v1, v1, 7, v150
	global_load_dwordx4 v[44:47], v0, s[42:43]
	global_load_dwordx4 v[48:51], v1, s[42:43]
	v_lshlrev_b32_e32 v0, 7, v68
	v_bfe_u32 v1, v68, 16, 16
	v_and_or_b32 v0, v0, s68, v150
	v_lshl_or_b32 v1, v1, 7, v150
	global_load_dwordx4 v[20:23], v0, s[42:43]
	global_load_dwordx4 v[24:27], v1, s[42:43]
	v_lshlrev_b32_e32 v0, 7, v69
	v_bfe_u32 v1, v69, 16, 16
	v_and_or_b32 v0, v0, s68, v150
	v_lshl_or_b32 v1, v1, 7, v150
	global_load_dwordx4 v[28:31], v0, s[42:43]
	global_load_dwordx4 v[32:35], v1, s[42:43]
	v_lshlrev_b32_e32 v0, 7, v70
	v_bfe_u32 v1, v70, 16, 16
	v_lshlrev_b32_e32 v8, 7, v71
	v_bfe_u32 v9, v71, 16, 16
	v_and_or_b32 v0, v0, s68, v150
	v_lshl_or_b32 v4, v1, 7, v150
	v_and_or_b32 v8, v8, s68, v150
	v_lshl_or_b32 v12, v9, 7, v150
	global_load_dwordx4 v[0:3], v0, s[42:43]
	s_nop 0
	global_load_dwordx4 v[4:7], v4, s[42:43]
	s_nop 0
	global_load_dwordx4 v[8:11], v8, s[42:43]
	s_nop 0
	global_load_dwordx4 v[16:19], v12, s[42:43]
	v_lshl_add_u32 v12, s52, 7, v187
	v_lshl_add_u64 v[68:69], v[166:167], 0, s[40:41]
	ds_read_b128 v[12:15], v12
	global_load_dword v220, v[68:69], off offset:1792
	global_load_dword v228, v[68:69], off sc1
	global_load_dword v227, v[68:69], off offset:256 sc1
	global_load_dword v226, v[68:69], off offset:512 sc1
	global_load_dword v225, v[68:69], off offset:768 sc1
	global_load_dword v224, v[68:69], off offset:1024 sc1
	global_load_dword v223, v[68:69], off offset:1280 sc1
	global_load_dword v222, v[68:69], off offset:1536 sc1
	v_lshl_add_u32 v68, s51, 8, v185
	ds_read_b128 v[72:75], v68 offset:768
	ds_read_b128 v[68:71], v68 offset:784
	v_perm_b32 v145, v132, v128, s71
	v_perm_b32 v128, v132, v128, s72
	v_perm_b32 v132, v140, v136, s71
	v_perm_b32 v136, v140, v136, s72
	v_perm_b32 v140, v132, v145, s73
	v_perm_b32 v132, v132, v145, s74
	v_mov_b32_e32 v145, 0
	v_dot4c_i32_i8_e32 v145, v132, v76
	v_perm_b32 v132, v136, v128, s73
	v_perm_b32 v128, v136, v128, s74
	v_dot4_i32_i8 v146, v132, v76, 0
	v_dot4_i32_i8 v147, v128, v76, 0
	v_perm_b32 v128, v133, v129, s71
	v_perm_b32 v132, v141, v137, s71
	v_perm_b32 v129, v133, v129, s72
	v_perm_b32 v133, v141, v137, s72
	v_perm_b32 v136, v132, v128, s73
	v_perm_b32 v128, v132, v128, s74
	v_dot4_i32_i8 v239, v128, v76, 0
	v_perm_b32 v128, v133, v129, s73
	v_dot4_i32_i8 v240, v128, v76, 0
	v_perm_b32 v128, v133, v129, s74
	v_dot4_i32_i8 v241, v128, v76, 0
	v_perm_b32 v128, v134, v130, s71
	v_perm_b32 v129, v134, v130, s72
	v_perm_b32 v130, v142, v138, s71
	v_perm_b32 v132, v142, v138, s72
	v_perm_b32 v133, v130, v128, s73
	v_perm_b32 v128, v130, v128, s74
	v_dot4_i32_i8 v243, v128, v76, 0
	v_perm_b32 v128, v132, v129, s73
	v_dot4_i32_i8 v244, v128, v76, 0
	v_perm_b32 v128, v132, v129, s74
	v_perm_b32 v129, v135, v131, s71
	v_perm_b32 v130, v143, v139, s71
	v_dot4_i32_i8 v242, v133, v76, 0
	v_dot4_i32_i8 v245, v128, v76, 0
	v_perm_b32 v131, v135, v131, s72
	v_perm_b32 v132, v143, v139, s72
	v_perm_b32 v133, v130, v129, s73
	v_perm_b32 v130, v130, v129, s74
	v_mov_b32_e32 v129, 0
	v_dot4_i32_i8 v128, v133, v76, 0
	v_dot4c_i32_i8_e32 v129, v130, v76
	v_perm_b32 v133, v132, v131, s73
	v_mov_b32_e32 v130, 0
	v_perm_b32 v132, v132, v131, s74
	v_mov_b32_e32 v131, 0
	v_dot4_i32_i8 v144, v140, v76, 0
	v_dot4_i32_i8 v238, v136, v76, 0
	v_dot4c_i32_i8_e32 v130, v133, v76
	v_dot4c_i32_i8_e32 v131, v132, v76
	v_perm_b32 v76, v116, v112, s71
	v_perm_b32 v112, v116, v112, s72
	v_perm_b32 v116, v124, v120, s71
	v_perm_b32 v120, v124, v120, s72
	v_perm_b32 v124, v116, v76, s73
	v_perm_b32 v76, v116, v76, s74
	v_dot4c_i32_i8_e32 v145, v76, v77
	v_perm_b32 v76, v120, v112, s73
	v_dot4c_i32_i8_e32 v146, v76, v77
	v_perm_b32 v76, v120, v112, s74
	v_dot4c_i32_i8_e32 v147, v76, v77
	v_perm_b32 v76, v117, v113, s71
	v_perm_b32 v112, v117, v113, s72
	v_perm_b32 v113, v125, v121, s71
	v_perm_b32 v116, v125, v121, s72
	v_perm_b32 v117, v113, v76, s73
	v_perm_b32 v76, v113, v76, s74
	v_dot4c_i32_i8_e32 v239, v76, v77
	v_perm_b32 v76, v116, v112, s73
	v_dot4c_i32_i8_e32 v240, v76, v77
	v_perm_b32 v76, v116, v112, s74
	v_dot4c_i32_i8_e32 v241, v76, v77
	v_perm_b32 v76, v118, v114, s71
	v_perm_b32 v113, v126, v122, s71
	v_perm_b32 v112, v118, v114, s72
	v_perm_b32 v114, v126, v122, s72
	v_perm_b32 v116, v113, v76, s73
	v_perm_b32 v76, v113, v76, s74
	v_dot4c_i32_i8_e32 v243, v76, v77
	v_perm_b32 v76, v114, v112, s73
	v_dot4c_i32_i8_e32 v244, v76, v77
	v_perm_b32 v76, v114, v112, s74
	v_dot4c_i32_i8_e32 v245, v76, v77
	v_perm_b32 v76, v119, v115, s71
	v_perm_b32 v113, v127, v123, s71
	v_perm_b32 v112, v119, v115, s72
	v_perm_b32 v114, v127, v123, s72
	v_perm_b32 v115, v113, v76, s73
	v_perm_b32 v76, v113, v76, s74
	v_dot4c_i32_i8_e32 v129, v76, v77
	v_perm_b32 v76, v114, v112, s73
	v_dot4c_i32_i8_e32 v130, v76, v77
	v_perm_b32 v76, v114, v112, s74
	v_dot4c_i32_i8_e32 v144, v124, v77
	v_dot4c_i32_i8_e32 v238, v117, v77
	v_dot4c_i32_i8_e32 v242, v116, v77
	v_dot4c_i32_i8_e32 v128, v115, v77
	v_dot4c_i32_i8_e32 v131, v76, v77
	v_perm_b32 v76, v100, v96, s71
	v_perm_b32 v77, v100, v96, s72
	v_perm_b32 v96, v108, v104, s71
	v_perm_b32 v100, v108, v104, s72
	v_perm_b32 v104, v96, v76, s73
	v_perm_b32 v76, v96, v76, s74
	v_dot4c_i32_i8_e32 v145, v76, v78
	v_perm_b32 v76, v100, v77, s73
	v_dot4c_i32_i8_e32 v146, v76, v78
	v_perm_b32 v76, v100, v77, s74
	v_dot4c_i32_i8_e32 v147, v76, v78
	v_perm_b32 v76, v101, v97, s71
	v_perm_b32 v96, v109, v105, s71
	v_perm_b32 v77, v101, v97, s72
	v_perm_b32 v97, v109, v105, s72
	v_perm_b32 v100, v96, v76, s73
	v_perm_b32 v76, v96, v76, s74
	v_dot4c_i32_i8_e32 v239, v76, v78
	v_perm_b32 v76, v97, v77, s73
	v_dot4c_i32_i8_e32 v240, v76, v78
	v_perm_b32 v76, v97, v77, s74
	v_dot4c_i32_i8_e32 v241, v76, v78
	v_perm_b32 v76, v102, v98, s71
	v_perm_b32 v96, v110, v106, s71
	v_perm_b32 v77, v102, v98, s72
	v_perm_b32 v97, v110, v106, s72
	v_perm_b32 v98, v96, v76, s73
	v_perm_b32 v76, v96, v76, s74
	v_dot4c_i32_i8_e32 v243, v76, v78
	v_perm_b32 v76, v97, v77, s73
	v_dot4c_i32_i8_e32 v244, v76, v78
	v_perm_b32 v76, v97, v77, s74
	v_dot4c_i32_i8_e32 v245, v76, v78
	v_perm_b32 v76, v103, v99, s71
	v_perm_b32 v96, v111, v107, s71
	v_dot4c_i32_i8_e32 v242, v98, v78
	v_perm_b32 v77, v103, v99, s72
	v_perm_b32 v97, v111, v107, s72
	v_perm_b32 v98, v96, v76, s73
	v_perm_b32 v76, v96, v76, s74
	v_dot4c_i32_i8_e32 v129, v76, v78
	v_perm_b32 v76, v97, v77, s73
	v_dot4c_i32_i8_e32 v130, v76, v78
	v_perm_b32 v76, v97, v77, s74
	v_dot4c_i32_i8_e32 v144, v104, v78
	v_dot4c_i32_i8_e32 v238, v100, v78
	v_dot4c_i32_i8_e32 v128, v98, v78
	v_dot4c_i32_i8_e32 v131, v76, v78
	v_perm_b32 v76, v84, v80, s71
	v_perm_b32 v78, v92, v88, s71
	v_perm_b32 v77, v84, v80, s72
	v_perm_b32 v80, v92, v88, s72
	v_perm_b32 v84, v78, v76, s73
	v_perm_b32 v76, v78, v76, s74
	v_dot4c_i32_i8_e32 v145, v76, v79
	v_perm_b32 v76, v80, v77, s73
	v_dot4c_i32_i8_e32 v146, v76, v79
	v_perm_b32 v76, v80, v77, s74
	v_dot4c_i32_i8_e32 v147, v76, v79
	v_perm_b32 v76, v85, v81, s71
	v_perm_b32 v78, v93, v89, s71
	v_perm_b32 v77, v85, v81, s72
	v_perm_b32 v80, v93, v89, s72
	v_perm_b32 v81, v78, v76, s73
	v_perm_b32 v76, v78, v76, s74
	v_dot4c_i32_i8_e32 v239, v76, v79
	v_perm_b32 v76, v80, v77, s73
	v_dot4c_i32_i8_e32 v240, v76, v79
	v_perm_b32 v76, v80, v77, s74
	v_dot4c_i32_i8_e32 v241, v76, v79
	v_perm_b32 v76, v86, v82, s71
	v_perm_b32 v78, v94, v90, s71
	v_dot4c_i32_i8_e32 v238, v81, v79
	v_perm_b32 v77, v86, v82, s72
	v_perm_b32 v80, v94, v90, s72
	v_perm_b32 v81, v78, v76, s73
	v_perm_b32 v76, v78, v76, s74
	v_dot4c_i32_i8_e32 v243, v76, v79
	v_perm_b32 v76, v80, v77, s73
	v_dot4c_i32_i8_e32 v244, v76, v79
	v_perm_b32 v76, v80, v77, s74
	v_dot4c_i32_i8_e32 v245, v76, v79
	v_perm_b32 v76, v87, v83, s71
	v_perm_b32 v78, v95, v91, s71
	v_dot4c_i32_i8_e32 v242, v81, v79
	v_perm_b32 v77, v87, v83, s72
	v_perm_b32 v80, v95, v91, s72
	v_perm_b32 v81, v78, v76, s73
	v_perm_b32 v76, v78, v76, s74
	v_dot4c_i32_i8_e32 v129, v76, v79
	v_perm_b32 v76, v80, v77, s73
	v_dot4c_i32_i8_e32 v144, v84, v79
	v_dot4c_i32_i8_e32 v130, v76, v79
	v_perm_b32 v76, v80, v77, s74
	v_dot4c_i32_i8_e32 v128, v81, v79
	v_dot4c_i32_i8_e32 v131, v76, v79
	ds_write_b128 v219, v[144:147] offset:2048
	ds_write_b128 v219, v[238:241] offset:2064
	ds_write_b128 v219, v[242:245] offset:2080
	ds_write_b128 v219, v[128:131] offset:2096
	ds_read2st64_b64 v[76:79], v188 offset0:4 offset1:5
	ds_read2st64_b64 v[80:83], v188 offset0:6 offset1:7
	v_lshlrev_b32_e32 v92, 16, v235
	v_and_b32_e32 v93, 0xffff0000, v235
	v_lshlrev_b32_e32 v94, 16, v234
	s_waitcnt lgkmcnt(1)
	v_add_u32_e32 v89, v78, v76
	v_add_u32_e32 v116, v79, v77
	ds_read2st64_b64 v[76:79], v188 offset0:8 offset1:9
	ds_read2st64_b64 v[84:87], v188 offset0:10 offset1:11
	global_load_dwordx2 v[106:107], v[162:163], off
	global_load_dwordx2 v[132:133], v[162:163], off offset:512
	global_load_dwordx2 v[134:135], v[162:163], off offset:1024
	global_load_dwordx2 v[136:137], v[162:163], off offset:1536
	global_load_dwordx2 v[138:139], v[162:163], off offset:2048
	global_load_dwordx2 v[140:141], v[162:163], off offset:2560
	global_load_dwordx2 v[142:143], v[162:163], off offset:3072
	global_load_dwordx2 v[126:127], v[162:163], off offset:3584
	s_waitcnt lgkmcnt(2)
	v_add3_u32 v80, v89, v80, v82
	v_and_b32_e32 v95, 0xffff0000, v234
	v_pk_mul_f32 v[108:109], v[92:93], v[92:93]
	s_waitcnt lgkmcnt(1)
	v_add3_u32 v76, v80, v76, v78
	v_pk_mul_f32 v[110:111], v[94:95], v[94:95]
	s_waitcnt lgkmcnt(0)
	v_add3_u32 v76, v76, v84, v86
	v_add_f32_e32 v86, v108, v109
	v_lshlrev_b32_e32 v96, 16, v233
	v_and_b32_e32 v97, 0xffff0000, v233
	v_add_f32_e32 v86, v86, v110
	v_pk_mul_f32 v[112:113], v[96:97], v[96:97]
	v_add_f32_e32 v86, v111, v86
	v_lshlrev_b32_e32 v98, 16, v232
	v_and_b32_e32 v99, 0xffff0000, v232
	v_add_f32_e32 v86, v112, v86
	v_pk_mul_f32 v[114:115], v[98:99], v[98:99]
	v_add3_u32 v81, v116, v81, v83
	v_add_f32_e32 v86, v113, v86
	v_mov_b32_e32 v88, s33
	v_lshlrev_b32_e32 v100, 16, v231
	v_and_b32_e32 v101, 0xffff0000, v231
	v_add3_u32 v77, v81, v77, v79
	v_add_f32_e32 v86, v114, v86
	ds_read_b32 v88, v88
	v_add3_u32 v77, v77, v85, v87
	v_pk_mul_f32 v[78:79], v[100:101], v[100:101]
	v_add_f32_e32 v86, v115, v86
	v_lshlrev_b32_e32 v102, 16, v230
	v_and_b32_e32 v103, 0xffff0000, v230
	v_cvt_f32_i32_e32 v77, v77
	v_cvt_f32_i32_e32 v76, v76
	v_add_f32_e32 v78, v78, v86
	v_pk_mul_f32 v[80:81], v[102:103], v[102:103]
	v_add_f32_e32 v78, v79, v78
	v_lshlrev_b32_e32 v104, 16, v229
	v_and_b32_e32 v105, 0xffff0000, v229
	v_add_f32_e32 v78, v80, v78
	v_lshlrev_b32_e32 v90, 16, v236
	v_and_b32_e32 v91, 0xffff0000, v236
	v_pk_mul_f32 v[82:83], v[104:105], v[104:105]
	v_add_f32_e32 v78, v81, v78
	s_waitcnt lgkmcnt(0)
	v_pk_fma_f32 v[76:77], v[88:89], v[76:77], v[90:91] op_sel_hi:[0,1,1]
	v_add_f32_e32 v78, v82, v78
	v_pk_mul_f32 v[84:85], v[76:77], v[76:77]
	v_add_f32_e32 v78, v83, v78
	v_add_f32_e32 v78, v78, v84
	v_add_f32_e32 v78, v85, v78
	ds_bpermute_b32 v79, v189, v78
	s_waitcnt lgkmcnt(0)
	v_add_f32_e32 v78, v78, v79
	ds_bpermute_b32 v79, v190, v78
	s_waitcnt lgkmcnt(0)
	v_add_f32_e32 v78, v78, v79
	ds_bpermute_b32 v79, v191, v78
	s_waitcnt lgkmcnt(0)
	v_add_f32_e32 v78, v78, v79
	ds_bpermute_b32 v79, v192, v78
	s_waitcnt lgkmcnt(0)
	v_add_f32_e32 v78, v78, v79
	ds_bpermute_b32 v79, v193, v78
	s_waitcnt lgkmcnt(0)
	v_add_f32_e32 v78, v78, v79
	ds_bpermute_b32 v79, v194, v78
	s_waitcnt lgkmcnt(0)
	v_add_f32_e32 v78, v78, v79
	v_fmamk_f32 v78, v78, 0x3a800000, v216
	v_mul_f32_e32 v79, 0x4b800000, v78
	v_cmp_gt_f32_e32 vcc, s75, v78
	s_nop 1
	v_cndmask_b32_e32 v78, v78, v79, vcc
	v_rsq_f32_e32 v80, v78
	v_lshl_add_u64 v[78:79], v[160:161], 0, s[0:1]
	v_mul_f32_e32 v81, 0x45800000, v80
	v_cndmask_b32_e32 v80, v80, v81, vcc
	v_pk_mul_f32 v[82:83], v[80:81], v[92:93] op_sel_hi:[0,1]
	s_waitcnt vmcnt(0)
	v_pk_mul_f32 v[82:83], v[106:107], v[82:83]
	global_store_dwordx2 v[78:79], v[82:83], off nt
	v_pk_mul_f32 v[84:85], v[80:81], v[94:95] op_sel_hi:[0,1]
	v_pk_mul_f32 v[76:77], v[76:77], v[80:81] op_sel_hi:[1,0]
	s_nop 0
	v_pk_mul_f32 v[82:83], v[132:133], v[84:85]
	global_store_dwordx2 v[78:79], v[82:83], off offset:512 nt
	v_pk_mul_f32 v[84:85], v[80:81], v[96:97] op_sel_hi:[0,1]
	s_nop 0
	v_pk_mul_f32 v[82:83], v[134:135], v[84:85]
	global_store_dwordx2 v[78:79], v[82:83], off offset:1024 nt
	v_pk_mul_f32 v[84:85], v[80:81], v[98:99] op_sel_hi:[0,1]
	s_nop 0
	v_pk_mul_f32 v[82:83], v[136:137], v[84:85]
	global_store_dwordx2 v[78:79], v[82:83], off offset:1536 nt
	v_pk_mul_f32 v[84:85], v[80:81], v[100:101] op_sel_hi:[0,1]
	s_nop 0
	v_pk_mul_f32 v[82:83], v[138:139], v[84:85]
	global_store_dwordx2 v[78:79], v[82:83], off offset:2048 nt
	v_pk_mul_f32 v[84:85], v[80:81], v[102:103] op_sel_hi:[0,1]
	s_nop 0
	v_pk_mul_f32 v[82:83], v[140:141], v[84:85]
	global_store_dwordx2 v[78:79], v[82:83], off offset:2560 nt
	v_pk_mul_f32 v[84:85], v[80:81], v[104:105] op_sel_hi:[0,1]
	s_nop 0
	v_pk_mul_f32 v[82:83], v[142:143], v[84:85]
	global_store_dwordx2 v[78:79], v[82:83], off offset:3072 nt
	s_nop 0
	v_pk_mul_f32 v[76:77], v[76:77], v[126:127]
	global_store_dwordx2 v[78:79], v[76:77], off offset:3584 nt
	v_lshl_add_u64 v[168:169], v[168:169], 0, s[46:47]
	v_add_u32_e32 v221, 0x100, v221
	s_mov_b32 s33, s50
	s_mov_b32 s76, s45
	s_cbranch_scc0 .LBB0_1396
	s_add_i32 s48, s80, s30
	s_add_i32 s44, s44, s65
	s_cmpk_gt_i32 s48, 0xff
	s_cbranch_scc0 .LBB0_1345
